# v35 + merge phase: the two per-token wave sums as six DPP adds (row_shr 1/2/4/8, row_bcast 15/31, total from lane 63 via an SGPR) instead of six ds_bpermute round trips
# speedup vs baseline: 1.0189x; 1.0010x over previous
; #define GAS __attribute__((address_space(1)))
; __device__ __forceinline__ unsigned pk2(float lo, float hi) { return f2bf(lo) | (f2bf(hi) << 16); }
; __device__ __forceinline__ float lane_read(float v, int src_lane) { return __builtin_bit_cast(float, __builtin_amdgcn_ds_bpermute(src_lane << 2, __builtin_bit_cast(int, v))); }
; __device__ __forceinline__ float wave_sum(float v, int lane) {
; #pragma unroll
;     for (int o = 1; o < 64; o <<= 1) v += lane_read(v, lane ^ o);
;     return v;
; }
; __device__ __forceinline__ void merge_phase(Frame& F, int l, bool with_ctx) {
;     ...
;         for (int tk = F.wave; tk < TI; tk += NWAVES) {
;             const size_t row = (size_t)(tok0 + tk);
;             const v4u r0 = *(const GAS v4u*)(A + row * 1024 + 8 * F.lane), r1 = *(const GAS v4u*)(A + row * 1024 + 512 + 8 * F.lane);
;             float v[16];
;             v[0] = bf2f(r0.x & 0xffff); v[1] = bf2f(r0.x >> 16); v[2] = bf2f(r0.y & 0xffff); v[3] = bf2f(r0.y >> 16); v[4] = bf2f(r0.z & 0xffff); v[5] = bf2f(r0.z >> 16); v[6] = bf2f(r0.w & 0xffff); v[7] = bf2f(r0.w >> 16);
;             v[8] = bf2f(r1.x & 0xffff); v[9] = bf2f(r1.x >> 16); v[10] = bf2f(r1.y & 0xffff); v[11] = bf2f(r1.y >> 16); v[12] = bf2f(r1.z & 0xffff); v[13] = bf2f(r1.z >> 16); v[14] = bf2f(r1.w & 0xffff); v[15] = bf2f(r1.w >> 16);
;             float ss = 0.f;
; #pragma unroll
;             for (int j = 0; j < 16; ++j) ss += v[j] * v[j];
;             const float rstd = 1.0f / sqrtf(wave_sum(ss, F.lane) * (1.0f / NAW) + EPS);
;             const f32x4 g0 = *(const GAS f32x4*)(gain + 8 * F.lane), g1 = *(const GAS f32x4*)(gain + 8 * F.lane + 4), g2 = *(const GAS f32x4*)(gain + 512 + 8 * F.lane), g3 = *(const GAS f32x4*)(gain + 512 + 8 * F.lane + 4);
;             v4u o0, o1;
;             o0.x = pk2(v[0] * rstd * g0.x, v[1] * rstd * g0.y); o0.y = pk2(v[2] * rstd * g0.z, v[3] * rstd * g0.w); o0.z = pk2(v[4] * rstd * g1.x, v[5] * rstd * g1.y); o0.w = pk2(v[6] * rstd * g1.z, v[7] * rstd * g1.w);
;             o1.x = pk2(v[8] * rstd * g2.x, v[9] * rstd * g2.y); o1.y = pk2(v[10] * rstd * g2.z, v[11] * rstd * g2.w); o1.z = pk2(v[12] * rstd * g3.x, v[13] * rstd * g3.y); o1.w = pk2(v[14] * rstd * g3.z, v[15] * rstd * g3.w);
;             *(GAS v4u*)(H + row * DM + 8 * F.lane) = o0; *(GAS v4u*)(H + row * DM + 512 + 8 * F.lane) = o1;
;         }
.LBB0_1076:
	v_lshl_add_u64 v[24:25], s[26:27], 0, v[14:15]
	s_mov_b32 s6, 0x44900000
	v_add_co_u32_e32 v28, vcc, s6, v24
	global_load_dwordx4 v[0:3], v[10:11], off offset:16
	global_load_dwordx4 v[4:7], v[10:11], off
	global_load_dwordx4 v[16:19], v[10:11], off offset:2064
	global_load_dwordx4 v[20:23], v[10:11], off offset:2048
	v_addc_co_u32_e32 v29, vcc, 0, v25, vcc
	global_load_dwordx4 v[24:27], v[28:29], off offset:1024
	s_add_i32 s3, s3, 8
	s_waitcnt vmcnt(0)
	v_mov_b32_e32 v68, v4
	v_mov_b32_e32 v69, v6
	v_mov_b32_e32 v39, v22
	v_mov_b32_e32 v22, v21
	v_mov_b32_e32 v38, v20
	v_lshlrev_b32_e32 v21, 16, v27
	v_and_b32_e32 v41, 0xffff0000, v27
	v_lshlrev_b32_e32 v31, 16, v25
	v_lshlrev_b32_e32 v30, 16, v24
	v_and_b32_e32 v33, 0xffff0000, v25
	v_and_b32_e32 v32, 0xffff0000, v24
	v_mov_b32_e32 v24, v41
	v_mov_b32_e32 v25, v21
	v_lshlrev_b32_e32 v20, 16, v26
	v_and_b32_e32 v40, 0xffff0000, v26
	v_pk_mul_f32 v[62:63], v[24:25], v[24:25]
	global_load_dwordx4 v[24:27], v[28:29], off
	v_mov_b32_e32 v6, v5
	v_pk_mul_f32 v[34:35], v[30:31], v[30:31]
	v_pk_mul_f32 v[36:37], v[32:33], v[32:33]
	s_waitcnt vmcnt(0)
	v_lshlrev_b32_e32 v29, 16, v25
	v_lshlrev_b32_e32 v28, 16, v24
	v_and_b32_e32 v25, 0xffff0000, v25
	v_and_b32_e32 v24, 0xffff0000, v24
	v_pk_mul_f32 v[64:65], v[28:29], v[28:29]
	v_pk_mul_f32 v[66:67], v[24:25], v[24:25]
	v_lshlrev_b32_e32 v5, 16, v27
	v_add_f32_e32 v61, v64, v66
	v_lshlrev_b32_e32 v4, 16, v26
	v_add_f32_e32 v61, v65, v61
	v_and_b32_e32 v27, 0xffff0000, v27
	v_and_b32_e32 v26, 0xffff0000, v26
	v_pk_mul_f32 v[70:71], v[4:5], v[4:5]
	v_add_f32_e32 v61, v67, v61
	v_pk_mul_f32 v[72:73], v[26:27], v[26:27]
	v_add_f32_e32 v61, v70, v61
	v_add_f32_e32 v61, v72, v61
	v_add_f32_e32 v61, v71, v61
	v_add_f32_e32 v61, v73, v61
	v_add_f32_e32 v34, v34, v61
	v_add_f32_e32 v34, v36, v34
	v_add_f32_e32 v34, v35, v34
	v_add_f32_e32 v34, v37, v34
	v_fmac_f32_e32 v34, v20, v20
	v_fmac_f32_e32 v34, v40, v40
	v_add_f32_e32 v34, v63, v34
	v_add_f32_e32 v34, v62, v34
	s_nop 1
	v_add_f32_dpp v34, v34, v34 row_shr:1 row_mask:0xf bank_mask:0xf bound_ctrl:0
	s_nop 1
	v_add_f32_dpp v34, v34, v34 row_shr:2 row_mask:0xf bank_mask:0xf bound_ctrl:0
	s_nop 1
	v_add_f32_dpp v34, v34, v34 row_shr:4 row_mask:0xf bank_mask:0xf bound_ctrl:0
	s_nop 1
	v_add_f32_dpp v34, v34, v34 row_shr:8 row_mask:0xf bank_mask:0xf bound_ctrl:0
	s_nop 1
	v_add_f32_dpp v34, v34, v34 row_bcast:15 row_mask:0xa bank_mask:0xf
	s_nop 1
	v_add_f32_dpp v34, v34, v34 row_bcast:31 row_mask:0xc bank_mask:0xf
	s_nop 0
	v_readlane_b32 s6, v34, 63
	s_nop 1
	v_mov_b32_e32 v34, s6
	v_fmamk_f32 v34, v34, 0x3a800000, v212
	v_cmp_gt_f32_e32 vcc, s60, v34
	v_mul_f32_e32 v35, 0x4f800000, v34
	s_nop 0
	v_cndmask_b32_e32 v34, v34, v35, vcc
	v_sqrt_f32_e32 v35, v34
	s_nop 0
	v_add_u32_e32 v36, -1, v35
	v_fma_f32 v37, -v36, v35, v34
	v_cmp_ge_f32_e64 s[6:7], 0, v37
	v_add_u32_e32 v37, 1, v35
	s_nop 0
	v_cndmask_b32_e64 v36, v35, v36, s[6:7]
	v_fma_f32 v35, -v37, v35, v34
	v_cmp_lt_f32_e64 s[6:7], 0, v35
	s_nop 1
	v_cndmask_b32_e64 v35, v36, v37, s[6:7]
	v_mul_f32_e32 v36, 0x37800000, v35
	v_cndmask_b32_e32 v35, v35, v36, vcc
	v_cmp_class_f32_e32 vcc, v34, v213
	s_nop 1
	v_cndmask_b32_e32 v34, v35, v34, vcc
	v_div_scale_f32 v35, s[6:7], v34, v34, 1.0
	v_rcp_f32_e32 v36, v35
	s_brev_b32 s6, 4
	v_fma_f32 v37, -v35, v36, 1.0
	v_fmac_f32_e32 v36, v37, v36
	v_div_scale_f32 v37, vcc, 1.0, v34, 1.0
	v_mul_f32_e32 v61, v37, v36
	v_fma_f32 v62, -v35, v61, v37
	v_fmac_f32_e32 v61, v62, v36
	v_fma_f32 v35, -v35, v61, v37
	v_div_fmas_f32 v35, v35, v36, v61
	v_div_fixup_f32 v34, v35, v34, 1.0
	v_pk_mul_f32 v[24:25], v[34:35], v[24:25] op_sel_hi:[0,1]
	v_pk_mul_f32 v[6:7], v[6:7], v[24:25]
	v_pk_mul_f32 v[4:5], v[34:35], v[4:5] op_sel_hi:[0,1]
	v_mov_b32_e32 v24, v0
	v_mov_b32_e32 v25, v2
	v_pk_mul_f32 v[4:5], v[24:25], v[4:5]
	v_pk_mul_f32 v[24:25], v[34:35], v[26:27] op_sel_hi:[0,1]
	v_mov_b32_e32 v2, v1
	v_pk_mul_f32 v[28:29], v[34:35], v[28:29] op_sel_hi:[0,1]
	v_pk_mul_f32 v[0:1], v[2:3], v[24:25]
	v_pk_mul_f32 v[28:29], v[68:69], v[28:29]
	v_bfe_u32 v2, v1, 16, 1
	v_bfe_u32 v3, v0, 16, 1
	v_bfe_u32 v24, v7, 16, 1
	v_bfe_u32 v25, v6, 16, 1
	v_add3_u32 v6, v6, v25, s61
	v_add3_u32 v7, v7, v24, s61
	v_add3_u32 v0, v0, v3, s61
	v_add3_u32 v1, v1, v2, s61
	v_bfe_u32 v2, v28, 16, 1
	v_bfe_u32 v3, v29, 16, 1
	v_bfe_u32 v24, v4, 16, 1
	v_bfe_u32 v25, v5, 16, 1
	v_add3_u32 v5, v5, v25, s61
	v_add3_u32 v4, v4, v24, s61
	v_add3_u32 v3, v29, v3, s61
	v_add3_u32 v2, v28, v2, s61
	v_lshrrev_b32_e32 v24, 16, v2
	v_lshrrev_b32_e32 v25, 16, v3
	v_lshrrev_b32_e32 v2, 16, v4
	v_lshrrev_b32_e32 v3, 16, v5
	v_and_or_b32 v3, v1, s86, v3
	v_and_or_b32 v2, v0, s86, v2
	v_and_or_b32 v1, v7, s86, v25
	v_and_or_b32 v0, v6, s86, v24
	v_pk_mul_f32 v[6:7], v[34:35], v[32:33] op_sel_hi:[0,1]
	v_pk_mul_f32 v[6:7], v[22:23], v[6:7]
	v_pk_mul_f32 v[20:21], v[34:35], v[20:21] op_sel_hi:[0,1]
	v_mov_b32_e32 v22, v16
	v_mov_b32_e32 v23, v18
	v_pk_mul_f32 v[20:21], v[22:23], v[20:21]
	v_pk_mul_f32 v[22:23], v[34:35], v[40:41] op_sel_hi:[0,1]
	v_mov_b32_e32 v18, v17
	v_pk_mul_f32 v[16:17], v[18:19], v[22:23]
	v_pk_mul_f32 v[4:5], v[34:35], v[30:31] op_sel_hi:[0,1]
	v_bfe_u32 v18, v17, 16, 1
	v_bfe_u32 v19, v16, 16, 1
	v_bfe_u32 v22, v7, 16, 1
	v_bfe_u32 v23, v6, 16, 1
	v_pk_mul_f32 v[4:5], v[38:39], v[4:5]
	v_add3_u32 v23, v6, v23, s61
	v_add3_u32 v22, v7, v22, s61
	v_add3_u32 v6, v16, v19, s61
	v_add3_u32 v7, v17, v18, s61
	v_bfe_u32 v18, v20, 16, 1
	v_bfe_u32 v19, v21, 16, 1
	v_bfe_u32 v16, v4, 16, 1
	v_bfe_u32 v17, v5, 16, 1
	v_add3_u32 v19, v21, v19, s61
	v_add3_u32 v18, v20, v18, s61
	v_add3_u32 v5, v5, v17, s61
	v_add3_u32 v4, v4, v16, s61
	v_lshrrev_b32_e32 v16, 16, v18
	v_lshrrev_b32_e32 v17, 16, v19
	v_and_or_b32 v7, v7, s86, v17
	v_and_or_b32 v6, v6, s86, v16
	v_lshl_add_u64 v[16:17], s[24:25], 0, v[14:15]
	s_add_u32 s24, s24, 0x8000
	s_addc_u32 s25, s25, 0
	s_add_u32 s26, s26, 0x4000
	v_add_co_u32_e32 v16, vcc, s6, v16
	s_addc_u32 s27, s27, 0
	v_lshrrev_b32_e32 v4, 16, v4
	v_lshrrev_b32_e32 v5, 16, v5
	v_addc_co_u32_e32 v17, vcc, 0, v17, vcc
	s_cmp_ge_i32 s3, s31
	v_and_or_b32 v5, v22, s86, v5
	v_and_or_b32 v4, v23, s86, v4
	global_store_dwordx4 v[16:17], v[0:3], off
	global_store_dwordx4 v[16:17], v[4:7], off offset:1024
	s_cbranch_scc0 .LBB0_1076

; #define GAS __attribute__((address_space(1)))
; __device__ __forceinline__ unsigned f2bf(float f) { unsigned u = __builtin_bit_cast(unsigned, f); return (u + 0x7fffu + ((u >> 16) & 1u)) >> 16; }
; __device__ __forceinline__ float lane_read(float v, int src_lane) { return __builtin_bit_cast(float, __builtin_amdgcn_ds_bpermute(src_lane << 2, __builtin_bit_cast(int, v))); }
; __device__ __forceinline__ float wave_sum(float v, int lane) {
; #pragma unroll
;     for (int o = 1; o < 64; o <<= 1) v += lane_read(v, lane ^ o);
;     return v;
; }
; __device__ __forceinline__ void merge_phase(Frame& F, int l, bool with_ctx) {
;     ...
;             for (int tk = F.wave; tk < TI; tk += NWAVES) {
;                 float vv[8]; float ss = 0.f;
; #pragma unroll
;                 for (int i = 0; i < 8; ++i) { const int chn = F.lane + 64 * i; int srow = chn;
;                     if (grp == 0) { const int cc = chn & 127; srow = (chn & ~127) + (cc <= 64 ? cc : 192 - cc); }
;                     vv[i] = tile[srow * 65 + tk]; ss += vv[i] * vv[i]; }
;                 const float rstd = 1.0f / sqrtf(wave_sum(ss, F.lane) * (1.0f / 512.0f) + EPS);
;                 GAS bf16* hp = H + (size_t)(tok0 + tk) * DM + NAW + grp * 512;
; #pragma unroll
;                 for (int i = 0; i < 8; ++i) { const int chn = F.lane + 64 * i; hp[chn] = (bf16)f2bf(vv[i] * rstd * gain[NAW + grp * 512 + chn]); }
;             }
.LBB0_1211:
	v_add_u32_e32 v26, s49, v23
	v_add_u32_e32 v25, s49, v24
	ds_read_b32 v28, v26
	ds_read2st64_b32 v[2:3], v25 offset1:130
	v_add_u32_e32 v27, s49, v22
	ds_read_b32 v29, v27
	v_add_u32_e32 v27, 0x10400, v25
	ds_read_b32 v30, v27
	v_add_u32_e32 v27, s49, v21
	s_waitcnt lgkmcnt(3)
	v_mul_f32_e32 v26, v28, v28
	ds_read_b32 v31, v27
	v_add_u32_e32 v25, 0x18600, v25
	s_waitcnt lgkmcnt(3)
	v_fmac_f32_e32 v26, v2, v2
	ds_read_b32 v25, v25
	v_add_u32_e32 v27, s49, v20
	v_fmac_f32_e32 v26, v3, v3
	ds_read_b32 v32, v27
	s_waitcnt lgkmcnt(4)
	v_fmac_f32_e32 v26, v29, v29
	s_waitcnt lgkmcnt(3)
	v_fmac_f32_e32 v26, v30, v30
	s_waitcnt lgkmcnt(2)
	v_fmac_f32_e32 v26, v31, v31
	s_waitcnt lgkmcnt(1)
	v_fmac_f32_e32 v26, v25, v25
	s_waitcnt lgkmcnt(0)
	v_fmac_f32_e32 v26, v32, v32
	s_nop 1
	v_add_u32_e32 v20, 32, v20
	v_add_u32_e32 v24, 32, v24
	v_add_u32_e32 v21, 32, v21
	v_add_u32_e32 v22, 32, v22
	v_add_f32_dpp v26, v26, v26 row_shr:1 row_mask:0xf bank_mask:0xf bound_ctrl:0
	s_nop 1
	v_add_u32_e32 v23, 32, v23
	v_add_f32_dpp v26, v26, v26 row_shr:2 row_mask:0xf bank_mask:0xf bound_ctrl:0
	s_nop 1
	v_add_f32_dpp v26, v26, v26 row_shr:4 row_mask:0xf bank_mask:0xf bound_ctrl:0
	s_nop 1
	v_add_f32_dpp v26, v26, v26 row_shr:8 row_mask:0xf bank_mask:0xf bound_ctrl:0
	s_nop 1
	v_add_f32_dpp v26, v26, v26 row_bcast:15 row_mask:0xa bank_mask:0xf
	s_nop 1
	v_add_f32_dpp v26, v26, v26 row_bcast:31 row_mask:0xc bank_mask:0xf
	s_nop 0
	v_readlane_b32 s6, v26, 63
	s_nop 1
	v_mov_b32_e32 v26, s6
	v_fmamk_f32 v26, v26, 0x3b000000, v212
	v_cmp_gt_f32_e32 vcc, s60, v26
	v_mul_f32_e32 v27, 0x4f800000, v26
	s_nop 0
	v_cndmask_b32_e32 v26, v26, v27, vcc
	v_sqrt_f32_e32 v27, v26
	s_nop 0
	v_add_u32_e32 v33, -1, v27
	v_fma_f32 v34, -v33, v27, v26
	v_cmp_ge_f32_e64 s[6:7], 0, v34
	v_add_u32_e32 v34, 1, v27
	s_nop 0
	v_cndmask_b32_e64 v33, v27, v33, s[6:7]
	v_fma_f32 v27, -v34, v27, v26
	v_cmp_lt_f32_e64 s[6:7], 0, v27
	s_nop 1
	v_cndmask_b32_e64 v27, v33, v34, s[6:7]
	v_mul_f32_e32 v33, 0x37800000, v27
	v_cndmask_b32_e32 v27, v27, v33, vcc
	v_cmp_class_f32_e32 vcc, v26, v213
	s_nop 1
	v_cndmask_b32_e32 v26, v27, v26, vcc
	v_div_scale_f32 v27, s[6:7], v26, v26, 1.0
	v_rcp_f32_e32 v33, v27
	s_add_i32 s6, s22, s23
	s_ashr_i32 s7, s6, 31
	s_lshl_b64 s[6:7], s[6:7], 12
	v_fma_f32 v34, -v27, v33, 1.0
	v_fmac_f32_e32 v33, v34, v33
	v_div_scale_f32 v34, vcc, 1.0, v26, 1.0
	v_mul_f32_e32 v35, v34, v33
	v_fma_f32 v36, -v27, v35, v34
	v_fmac_f32_e32 v35, v36, v33
	v_fma_f32 v27, -v27, v35, v34
	v_div_fmas_f32 v27, v27, v33, v35
	v_div_fixup_f32 v33, v27, v26, 1.0
	v_mul_f32_e32 v2, v2, v33
	v_mul_f32_e32 v2, v4, v2
	v_bfe_u32 v26, v2, 16, 1
	v_add3_u32 v2, v2, v26, s61
	v_lshl_add_u64 v[26:27], v[0:1], 0, s[6:7]
	global_store_short_d16_hi v[26:27], v2, off offset:2048
	v_mul_f32_e32 v2, v28, v33
	v_mul_f32_e32 v2, v5, v2
	v_bfe_u32 v28, v2, 16, 1
	v_add3_u32 v2, v2, v28, s61
	global_store_short_d16_hi v[26:27], v2, off offset:2176
	v_mul_f32_e32 v2, v3, v33
	v_mul_f32_e32 v2, v6, v2
	v_bfe_u32 v3, v2, 16, 1
	v_add3_u32 v2, v2, v3, s61
	global_store_short_d16_hi v[26:27], v2, off offset:2304
	v_mul_f32_e32 v2, v29, v33
	v_mul_f32_e32 v2, v7, v2
	v_bfe_u32 v3, v2, 16, 1
	v_add3_u32 v2, v2, v3, s61
	global_store_short_d16_hi v[26:27], v2, off offset:2432
	v_mul_f32_e32 v2, v30, v33
	v_mul_f32_e32 v2, v16, v2
	v_bfe_u32 v3, v2, 16, 1
	v_add3_u32 v2, v2, v3, s61
	global_store_short_d16_hi v[26:27], v2, off offset:2560
	v_mul_f32_e32 v2, v31, v33
	v_mul_f32_e32 v2, v17, v2
	v_bfe_u32 v3, v2, 16, 1
	v_add3_u32 v2, v2, v3, s61
	global_store_short_d16_hi v[26:27], v2, off offset:2688
	v_mul_f32_e32 v2, v25, v33
	v_mul_f32_e32 v2, v18, v2
	v_bfe_u32 v3, v2, 16, 1
	v_add3_u32 v2, v2, v3, s61
	global_store_short_d16_hi v[26:27], v2, off offset:2816
	v_mul_f32_e32 v2, v32, v33
	v_mul_f32_e32 v2, v19, v2
	v_bfe_u32 v3, v2, 16, 1
	s_add_i32 s23, s23, 8
	v_add3_u32 v2, v2, v3, s61
	s_cmp_ge_i32 s23, s31
	global_store_short_d16_hi v[26:27], v2, off offset:2944
	s_cbranch_scc0 .LBB0_1211
	s_branch .LBB0_1078
